# baseline (speedup 1.0000x reference)
; __device__ void phase_nsa(const Params& p, char* smem) {
;   int* slot = (int*)(smem + SMEM_BYTES - 16);
;   for (;;) {
;     __syncthreads();
;     if (threadIdx.x == 0) *slot = atomicAdd(p.qctr, 1);
;     __syncthreads();
;     const int it = *slot;
.LBB0_237:
	s_cmp_lg_u32 s80, 3
	v_readlane_b32 s2, v252, 36
	s_cselect_b64 s[0:1], -1, 0
	v_readlane_b32 s3, v252, 37
	s_and_b64 s[0:1], s[2:3], s[0:1]
	s_and_b64 vcc, exec, s[0:1]
	s_cbranch_vccnz .LBB0_364
	v_writelane_b32 v252, s80, 40
	s_waitcnt lgkmcnt(0)
	v_writelane_b32 v252, s84, 41
	v_and_b32_e32 v1, 0x3ff, v0
	v_cmp_eq_u32_e64 s[0:1], 0, v1
	v_writelane_b32 v252, s85, 42
	v_writelane_b32 v252, s86, 43
	v_writelane_b32 v252, s87, 44
	v_writelane_b32 v252, s88, 45
	v_writelane_b32 v252, s89, 46
	v_writelane_b32 v252, s90, 47
	v_writelane_b32 v252, s91, 48
	v_writelane_b32 v252, s0, 49
	s_movk_i32 s20, 0xc000
	s_mov_b32 s58, 0x41300000
	v_writelane_b32 v252, s1, 50
	s_add_u32 s0, s34, 0xffffc000
	s_mov_b32 s62, 0x42040000
	s_mov_b32 s82, 0x40400000
	s_mov_b32 s80, 0x420c0000
	s_mov_b32 s6, 0x41100000
	s_mov_b32 s94, 0x42240000
	s_mov_b32 s90, 0x422c0000
	s_mov_b32 s42, 0x41880000
	s_mov_b32 s50, 0x42440000
	s_mov_b32 s84, 0x41980000
	s_mov_b32 s86, 0x424c0000
	s_mov_b32 s88, 0x41c80000
	s_mov_b32 s92, 0x42640000
	v_mbcnt_lo_u32_b32 v2, -1, 0
	s_mov_b32 s19, 0
	s_mov_b32 s21, -1
	v_writelane_b32 v252, s0, 51
	s_addc_u32 s0, s35, -1
	v_mov_b32_e32 v3, 0
	v_mov_b32_e32 v167, 0x21ff0
	s_movk_i32 s33, 0x6200
	s_movk_i32 s4, 0x5000
	s_movk_i32 s25, 0x3100
	s_mov_b32 s23, 0x8000
	s_mov_b64 s[54:55], 0x188800
	s_mov_b64 s[56:57], 0x188900
	s_mov_b32 s59, 0x41800000
	s_mov_b32 s60, 0x3e0293ee
	s_mov_b32 s63, 0x42080000
	s_mov_b32 s83, 0x41000000
	s_mov_b32 s81, 0x42200000
	s_mov_b32 s7, 0x41200000
	s_mov_b32 s95, 0x42280000
	s_mov_b32 s91, 0x42400000
	s_mov_b32 s43, 0x41900000
	s_mov_b32 s51, 0x42480000
	s_mov_b32 s85, 0x41c00000
	s_mov_b32 s87, 0x42600000
	s_mov_b32 s89, 0x41d00000
	s_mov_b32 s93, 0x42680000
	v_mov_b32_e32 v176, 0x20c00
	v_mov_b32_e32 v177, 0x20c10
	v_mov_b32_e32 v164, 1.0
	v_mov_b32_e32 v178, 0x20000
	v_mov_b32_e32 v179, 0x10000
	v_mov_b32_e32 v180, 0x42800000
	v_not_b32_e32 v181, 63
	v_mov_b32_e32 v182, 0x6000
	v_mov_b32_e32 v183, 0xff800000
	v_mov_b32_e32 v184, 0x42000000
	v_mov_b32_e32 v185, 0xff
	v_mbcnt_hi_u32_b32 v186, -1, v2
	v_mov_b32_e32 v187, 0x20400
	v_mov_b32_e32 v188, 0x6002
	v_mov_b32_e32 v189, 0x20d20
	v_mov_b32_e32 v190, 0xfffe7960
	v_mov_b32_e32 v191, 0x3e8
	v_mov_b32_e32 v192, 0x6004
	v_mov_b32_e32 v193, 0x180
	v_writelane_b32 v252, s0, 52
	v_readlane_b32 s98, v252, 49
	v_readlane_b32 s99, v252, 50
	s_nop 0
	s_and_saveexec_b64 s[100:101], s[98:99]
	s_cbranch_execz .Lpf_skip0
	v_readlane_b32 s98, v252, 47
	v_readlane_b32 s99, v252, 48
	v_mov_b32_e32 v250, 1
	v_mov_b32_e32 v249, 0
	s_nop 5
	global_atomic_add v251, v249, v250, s[98:99] sc0
.Lpf_skip0:
	s_mov_b64 exec, s[100:101]
	s_branch .LBB0_242

; __device__ void phase_nsa(const Params& p, char* smem) {
;     ...
;   for (;;) {
;     __syncthreads();
;     if (threadIdx.x == 0) *slot = atomicAdd(p.qctr, 1);
;     __syncthreads();
;     const int it = *slot;
.LBB0_242:
	s_barrier
	s_mov_b64 s[2:3], exec
	v_readlane_b32 s0, v252, 49
	v_readlane_b32 s1, v252, 50
	s_and_b64 s[0:1], s[2:3], s[0:1]
	s_mov_b64 exec, s[0:1]
	s_cbranch_execz .LBB0_246
	s_mov_b64 s[10:11], exec
	v_mbcnt_lo_u32_b32 v2, s10, 0
	v_mbcnt_hi_u32_b32 v2, s11, v2
	v_cmp_eq_u32_e32 vcc, 0, v2
	s_and_saveexec_b64 s[8:9], vcc
	s_cbranch_execz .LBB0_245
	s_bcnt1_i32_b64 s0, s[10:11]
	v_readlane_b32 s64, v252, 41
	v_mov_b32_e32 v4, s0
	v_readlane_b32 s70, v252, 47
	v_readlane_b32 s71, v252, 48
	v_readlane_b32 s65, v252, 42
	v_readlane_b32 s66, v252, 43
	v_readlane_b32 s67, v252, 44
	v_readlane_b32 s68, v252, 45
	v_readlane_b32 s69, v252, 46
	s_waitcnt vmcnt(0)
	v_mov_b32_e32 v4, v251

; __device__ void memx_item(const Params& p, int qblk, int hm, char* smem) {
;   int tid = threadIdx.x; asm volatile("" : "+v"(tid) :: "memory");
;   const int wid = tid >> 6, lane = tid & 63, r32 = lane & 31, hi = lane >> 5, rb = wid & 3, dh = wid >> 2;
;   const long t = (long)qblk * 128 + 32 * rb + r32;
;   constexpr float C = 0.0625f * LOG2E;
;   bf16x8 qr[16];
;   { const bf16* Qw = p.P + t * LDP + C_QM + hm * 256 + hi * 8;
; #pragma unroll
;     for (int d0 = 0; d0 < 16; ++d0) qr[d0] = ld8(Qw + d0 * 16); }
; __device__ void phase_nsa(const Params& p, char* smem) {
;     ...
;     const int it = *slot;
;     if (it >= 1024 + 512) break;
;     if (it < 1024) { const int g = 3 - (it >> 8), qb = 255 - (it & 255); nsa_item(p, qb, g, smem); }
;     else { const int j = it - 1024; memx_item(p, j >> 2, j & 3, smem); }
.LBB0_246:
	s_or_b64 exec, exec, s[2:3]
	s_waitcnt lgkmcnt(0)
	s_barrier
	ds_read_b32 v2, v167
	s_movk_i32 s0, 0x5ff
	s_mov_b64 s[2:3], -1
	s_waitcnt lgkmcnt(0)
	v_cmp_lt_i32_e32 vcc, s0, v2
	v_readfirstlane_b32 s14, v2
	s_cbranch_vccnz .LBB0_241
	s_cmpk_gt_i32 s14, 0x3ff
	s_cbranch_scc0 .LBB0_255
	v_readlane_b32 s98, v252, 49
	v_readlane_b32 s99, v252, 50
	s_nop 0
	s_and_saveexec_b64 s[100:101], s[98:99]
	s_cbranch_execz .Lpf_skip1
	v_readlane_b32 s98, v252, 47
	v_readlane_b32 s99, v252, 48
	v_mov_b32_e32 v250, 1
	v_mov_b32_e32 v249, 0
	s_nop 5
	global_atomic_add v251, v249, v250, s[98:99] sc0
.Lpf_skip1:
	s_mov_b64 exec, s[100:101]
	v_mov_b32_e32 v200, v1
	s_lshl_b32 s0, s14, 5
	v_ashrrev_i32_e32 v197, 6, v200
	s_and_b32 s0, s0, 0x7fffff80
	v_lshlrev_b32_e32 v201, 5, v197
	s_addk_i32 s0, 0x8000
	v_and_b32_e32 v2, 0x60, v201
	v_and_b32_e32 v196, 31, v200
	v_or_b32_e32 v165, s0, v2
	v_or_b32_e32 v2, v165, v196
	s_lshl_b32 s0, s14, 8
	v_mul_lo_u32 v2, v2, s33
	s_and_b32 s0, s0, 0x300
	v_bfe_u32 v198, v200, 5, 1
	v_lshl_add_u64 v[4:5], s[46:47], 0, v[2:3]
	s_lshl_b32 s18, s0, 1
	v_lshl_add_u64 v[4:5], v[4:5], 0, s[18:19]
	v_lshlrev_b32_e32 v2, 4, v198
	v_lshl_add_u64 v[4:5], v[4:5], 0, v[2:3]
	s_mov_b64 s[2:3], 0x5000
	v_readlane_b32 s64, v252, 18
	v_lshl_add_u64 v[6:7], v[4:5], 0, s[2:3]
	v_add_co_u32_e32 v4, vcc, s4, v4
	v_readlane_b32 s66, v252, 20
	s_nop 0
	v_addc_co_u32_e32 v5, vcc, 0, v5, vcc
	global_load_dwordx4 v[100:103], v[6:7], off offset:32
	global_load_dwordx4 v[104:107], v[6:7], off offset:64
	global_load_dwordx4 v[108:111], v[6:7], off offset:96
	global_load_dwordx4 v[112:115], v[6:7], off offset:128
	global_load_dwordx4 v[116:119], v[6:7], off offset:160
	global_load_dwordx4 v[120:123], v[6:7], off offset:192
	global_load_dwordx4 v[124:127], v[6:7], off offset:224
	global_load_dwordx4 v[128:131], v[6:7], off offset:256
	global_load_dwordx4 v[132:135], v[6:7], off offset:288
	global_load_dwordx4 v[136:139], v[6:7], off offset:320
	global_load_dwordx4 v[140:143], v[6:7], off offset:352
	global_load_dwordx4 v[144:147], v[6:7], off offset:384
	global_load_dwordx4 v[148:151], v[6:7], off offset:416
	global_load_dwordx4 v[152:155], v[6:7], off offset:448
	global_load_dwordx4 v[156:159], v[4:5], off
	global_load_dwordx4 v[160:163], v[6:7], off offset:480
	v_readlane_b32 s67, v252, 21
	s_add_u32 s2, s66, s18
	v_readfirstlane_b32 s1, v200
	v_lshrrev_b32_e32 v12, 5, v200
	v_ashrrev_i32_e32 v4, 4, v200
	v_add_u32_e32 v10, 0x200, v200
	s_addc_u32 s3, s67, 0
	v_and_b32_e32 v8, 15, v200
	v_and_b32_e32 v9, 8, v12
	v_and_b32_e32 v5, 7, v4
	s_lshl_b32 s1, s1, 4
	v_ashrrev_i32_e32 v10, 4, v10
	v_bitop3_b32 v5, v5, v8, v9 bitop3:0x36
	v_mul_lo_u32 v4, v4, s33
	s_and_b32 s1, s1, 0xfffffc00
	v_and_b32_e32 v11, 7, v10
	v_lshl_or_b32 v4, v5, 4, v4
	v_mov_b32_e32 v5, v3
	s_mov_b32 m0, s1
	v_bitop3_b32 v8, v11, v8, v9 bitop3:0x36
	v_mul_lo_u32 v9, v10, s33
	s_barrier
; #define LDS_AS3(ptr) ((__attribute__((address_space(3))) unsigned*)(ptr))
; __device__ __forceinline__ void dma_k(const bf16* __restrict__ g, int ld, char* Kl, int tid) {
;   const int widu = __builtin_amdgcn_readfirstlane(tid >> 6);
; #pragma unroll
;   for (int i = 0; i < 2; ++i) { const int s_ = tid + 512 * i, row = s_ >> 4, ch = (s_ & 15) ^ KSWZF(row);
;     const unsigned offb = (unsigned)(row * ld + ch * 8) * 2u;
;     __builtin_amdgcn_global_load_lds((const unsigned*)((const char*)g + offb), LDS_AS3(Kl + (widu * 64 + 512 * i) * 16), 16, 0, 0); }
; }
; __device__ __forceinline__ void dma_v(const bf16* __restrict__ g, int ld, char* Vl, int tid) {
;   const int widu = __builtin_amdgcn_readfirstlane(tid >> 6);
; #pragma unroll
;   for (int i = 0; i < 2; ++i) { const int s_ = tid + 512 * i, c = ((s_ >> 5) & 3) * 32 + (s_ & 3) * 8, kk = ((s_ >> 7) & 7) * 8 + ((s_ >> 2) & 7);
;     const int k = (kk & ~0xC) | ((kk & 4) << 1) | ((kk & 8) >> 1);
;     const unsigned offb = (unsigned)(k * ld + c) * 2u;
;     __builtin_amdgcn_global_load_lds((const unsigned*)((const char*)g + offb), LDS_AS3(Vl + (widu * 64 + 512 * i) * 16), 16, 0, 0); }
; }
; __device__ void memx_item(const Params& p, int qblk, int hm, char* smem) {
;   int tid = threadIdx.x; asm volatile("" : "+v"(tid) :: "memory");
;   const int wid = tid >> 6, lane = tid & 63, r32 = lane & 31, hi = lane >> 5, rb = wid & 3, dh = wid >> 2;
;   const long t = (long)qblk * 128 + 32 * rb + r32;
;   constexpr float C = 0.0625f * LOG2E;
;   bf16x8 qr[16];
;   { const bf16* Qw = p.P + t * LDP + C_QM + hm * 256 + hi * 8;
; #pragma unroll
;     for (int d0 = 0; d0 < 16; ++d0) qr[d0] = ld8(Qw + d0 * 16); }
;   const bf16* Kg = p.kvm + hm * 256; const bf16* Vg = p.kvm + 1024 + hm * 256;
;   auto issue = [&](int kt) { char* st = smem + (kt & 1) * 65536; const bf16* kp = Kg + (long)kt * 64 * LDP; const bf16* vp = Vg + (long)kt * 64 * LDP;
;     dma_k(kp, LDP, st, tid); dma_k(kp + 128, LDP, st + 16384, tid); dma_v(vp, LDP, st + 32768, tid); dma_v(vp + 128, LDP, st + 49152, tid); };
;   f32x16 o[4] = {}; f32x16 p0, p1; bf16x8 pa0, pa1, pa2, pa3;
;   float l = 0.f;
;   __syncthreads();
;   issue(0);
	v_lshl_add_u64 v[6:7], s[2:3], 0, v[4:5]
	global_load_lds_dwordx4 v4, s[2:3]
	v_lshl_or_b32 v8, v8, 4, v9
	v_mov_b32_e32 v9, v3
	s_add_i32 m0, s1, 0x2000
	s_mov_b64 s[8:9], 0x100
	v_lshl_add_u64 v[10:11], s[2:3], 0, v[8:9]
	global_load_lds_dwordx4 v8, s[2:3]
	v_lshl_add_u64 v[6:7], v[6:7], 0, s[8:9]
	s_add_i32 m0, s1, 0x4000
	v_lshlrev_b32_e32 v199, 3, v200
	global_load_lds_dwordx4 v[6:7], off
	v_lshl_add_u64 v[6:7], v[10:11], 0, s[8:9]
	s_add_i32 m0, s1, 0x6000
	v_lshrrev_b32_e32 v10, 4, v200
	global_load_lds_dwordx4 v[6:7], off
	v_bfe_u32 v6, v200, 2, 2
	v_and_b32_e32 v7, 4, v12
	v_and_b32_e32 v10, 48, v10
	v_or3_b32 v12, v7, v6, v10
	v_lshrrev_b32_e32 v6, 1, v200
	v_and_b32_e32 v16, 8, v6
	v_and_b32_e32 v14, 0x60, v200
	v_and_b32_e32 v15, 24, v199
	v_or_b32_e32 v6, v12, v16
	v_or_b32_e32 v13, v15, v14
	v_mul_u32_u24_e32 v17, 0x3100, v6
	v_or_b32_e32 v6, v17, v13
	v_lshlrev_b32_e32 v6, 1, v6
	v_mov_b32_e32 v7, v3
	v_lshl_add_u64 v[6:7], s[2:3], 0, v[6:7]
	s_mov_b64 s[8:9], 0x800
	v_lshl_add_u64 v[10:11], v[6:7], 0, s[8:9]
	s_add_i32 m0, s1, 0x8000
	v_and_b32_e32 v194, 63, v200
	global_load_lds_dwordx4 v[10:11], off
	v_bitop3_b32 v10, v12, 32, v16 bitop3:0x36
	v_mul_u32_u24_e32 v18, 0x3100, v10
	v_or_b32_e32 v10, v18, v13
	v_lshlrev_b32_e32 v10, 1, v10
	v_mov_b32_e32 v11, v3
	v_lshl_add_u64 v[10:11], s[2:3], 0, v[10:11]
	v_lshl_add_u64 v[12:13], v[10:11], 0, s[8:9]
	s_add_i32 m0, s1, 0xa000
	s_mov_b64 s[2:3], 0x900
	global_load_lds_dwordx4 v[12:13], off
	v_lshl_add_u64 v[6:7], v[6:7], 0, s[2:3]
	s_add_i32 m0, s1, 0xc000
	v_ashrrev_i32_e32 v195, 8, v200
	global_load_lds_dwordx4 v[6:7], off
	v_lshl_add_u64 v[6:7], v[10:11], 0, s[2:3]
	s_add_i32 m0, s1, 0xe000
	v_or_b32_e32 v10, 32, v2
	global_load_lds_dwordx4 v[6:7], off
	v_and_or_b32 v7, v200, 7, v16
	v_lshlrev_b32_e32 v6, 8, v196
	v_lshlrev_b32_e32 v7, 4, v7
	v_bitop3_b32 v203, v10, v6, v7 bitop3:0xde
	v_or_b32_e32 v10, 64, v2
	v_bitop3_b32 v204, v10, v6, v7 bitop3:0xde
	v_or_b32_e32 v10, 0x60, v2
	v_bitop3_b32 v205, v10, v6, v7 bitop3:0xde
	v_or_b32_e32 v10, 0x80, v2
	v_bitop3_b32 v206, v10, v6, v7 bitop3:0xde
	v_or_b32_e32 v10, 0xa0, v2
	v_bitop3_b32 v207, v10, v6, v7 bitop3:0xde
	v_or_b32_e32 v10, 0xc0, v2
	v_bitop3_b32 v208, v10, v6, v7 bitop3:0xde
	v_or_b32_e32 v10, 0xe0, v2
	v_bitop3_b32 v202, v7, v6, v2 bitop3:0xde
	v_bitop3_b32 v209, v10, v6, v7 bitop3:0xde
	v_lshlrev_b32_e32 v7, 4, v200
	v_lshlrev_b32_e32 v6, 3, v194
	v_and_b32_e32 v7, 0xc0, v7
	v_lshlrev_b32_e32 v10, 1, v200
	s_and_b32 s1, s14, 3
	v_and_or_b32 v7, v6, 24, v7
	v_and_b32_e32 v10, 32, v10
	v_and_b32_e32 v6, 0x100, v6
	s_lshl_b32 s1, s1, 9
	v_or3_b32 v210, v7, v10, v6
	v_or3_b32 v6, v18, v14, v15
	s_add_u32 s2, s66, s1
	v_lshlrev_b32_e32 v6, 1, v6
	v_mov_b32_e32 v7, v3
	s_addc_u32 s3, s67, 0
	v_lshl_add_u64 v[168:169], s[2:3], 0, v[6:7]
	v_or3_b32 v6, v17, v14, v15
	v_lshlrev_b32_e32 v6, 1, v6
	v_mov_b32_e32 v211, 0
	v_lshlrev_b32_e32 v166, 14, v195
	v_lshl_add_u64 v[170:171], s[2:3], 0, v[6:7]
	v_lshl_add_u64 v[172:173], s[2:3], 0, v[4:5]
	v_lshl_add_u64 v[174:175], s[2:3], 0, v[8:9]
	s_mov_b64 s[8:9], 0
	s_mov_b32 s1, 0x10000
	v_mov_b32_e32 v4, 0
	v_mov_b32_e32 v5, v211
	v_mov_b32_e32 v6, v211
	v_mov_b32_e32 v7, v211
	v_mov_b32_e32 v8, v211
	v_mov_b32_e32 v9, v211
	v_mov_b32_e32 v10, v211
	v_mov_b32_e32 v11, v211
	v_mov_b32_e32 v12, v211
	v_mov_b32_e32 v13, v211
	v_mov_b32_e32 v14, v211
	v_mov_b32_e32 v15, v211
	v_mov_b32_e32 v16, v211
	v_mov_b32_e32 v17, v211
	v_mov_b32_e32 v18, v211
	v_mov_b32_e32 v19, v211
	v_mov_b32_e32 v20, 0
	v_mov_b32_e32 v21, v211
	v_mov_b32_e32 v22, v211
	v_mov_b32_e32 v23, v211
	v_mov_b32_e32 v24, v211
	v_mov_b32_e32 v25, v211
	v_mov_b32_e32 v26, v211
	v_mov_b32_e32 v27, v211
	v_mov_b32_e32 v28, v211
	v_mov_b32_e32 v29, v211
	v_mov_b32_e32 v30, v211
	v_mov_b32_e32 v31, v211
	v_mov_b32_e32 v32, v211
	v_mov_b32_e32 v33, v211
	v_mov_b32_e32 v34, v211
	v_mov_b32_e32 v35, v211
	v_mov_b32_e32 v36, 0
	v_mov_b32_e32 v37, v211
	v_mov_b32_e32 v38, v211
	v_mov_b32_e32 v39, v211
	v_mov_b32_e32 v40, v211
	v_mov_b32_e32 v41, v211
	v_mov_b32_e32 v42, v211
	v_mov_b32_e32 v43, v211
	v_mov_b32_e32 v44, v211
	v_mov_b32_e32 v45, v211
	v_mov_b32_e32 v46, v211
	v_mov_b32_e32 v47, v211
	v_mov_b32_e32 v48, v211
	v_mov_b32_e32 v49, v211
	v_mov_b32_e32 v50, v211
	v_mov_b32_e32 v51, v211
	v_mov_b32_e32 v52, 0
	v_mov_b32_e32 v53, v211
	v_mov_b32_e32 v54, v211
	v_mov_b32_e32 v55, v211
	v_mov_b32_e32 v56, v211
	v_mov_b32_e32 v57, v211
	v_mov_b32_e32 v58, v211
	v_mov_b32_e32 v59, v211
	v_mov_b32_e32 v60, v211
	v_mov_b32_e32 v61, v211
	v_mov_b32_e32 v62, v211
	v_mov_b32_e32 v63, v211
	v_mov_b32_e32 v64, v211
	v_mov_b32_e32 v65, v211
	v_mov_b32_e32 v66, v211
	v_mov_b32_e32 v67, v211
	s_mov_b64 s[10:11], 0x188000
	s_mov_b64 s[12:13], 0x188100
	v_readlane_b32 s65, v252, 19
	v_readlane_b32 s68, v252, 22
	v_readlane_b32 s69, v252, 23
	v_readlane_b32 s70, v252, 24
	v_readlane_b32 s71, v252, 25
	v_readlane_b32 s72, v252, 26
	v_readlane_b32 s73, v252, 27
	v_readlane_b32 s74, v252, 28
	v_readlane_b32 s75, v252, 29
	v_readlane_b32 s76, v252, 30
	v_readlane_b32 s77, v252, 31
	v_readlane_b32 s78, v252, 32
	v_readlane_b32 s79, v252, 33
	s_waitcnt vmcnt(0)
	s_branch .LBB0_250

; __device__ __forceinline__ void unpark_fma(f32x16* o, const char* pk, int lane, const f32x4* f4) {
; #pragma unroll
;   for (int d0 = 0; d0 < 4; ++d0)
; #pragma unroll
;     for (int a = 0; a < 4; ++a) { const u32x2 w = *reinterpret_cast<const u32x2*>(pk + ((d0 * 4 + a) * 64 + lane) * 8);
;       o[d0][4 * a + 0] = fmaf(o[d0][4 * a + 0], f4[a][0], __uint_as_float(w[0] << 16));
;       o[d0][4 * a + 1] = fmaf(o[d0][4 * a + 1], f4[a][1], __uint_as_float(w[0] & 0xffff0000u));
;       o[d0][4 * a + 2] = fmaf(o[d0][4 * a + 2], f4[a][2], __uint_as_float(w[1] << 16));
;       o[d0][4 * a + 3] = fmaf(o[d0][4 * a + 3], f4[a][3], __uint_as_float(w[1] & 0xffff0000u)); }
; }
; template <int MODE>
; __device__ __forceinline__ void nsa_single(const Params& p, const LaneId& L, int q0, int g, int ntiles, int first, char* smem, const bf16x8* qr, float gate, f32x16* o) {
;     ...
;   { const float f = (l > 0.f) ? gate / l : 0.f; f32x4 f4[4]; row_bcast(fac, L, f, f4); unpark_fma(o, pk, L.lane, f4); }
;   __syncthreads();
.LBB0_339:
	s_or_b64 exec, exec, s[8:9]
	v_add_u32_e32 v2, v141, v142
	ds_read2st64_b64 v[84:87], v2 offset1:1
	ds_read_b128 v[80:83], v146
	ds_read_b128 v[76:79], v146 offset:32
	ds_read_b128 v[72:75], v146 offset:64
	ds_read_b128 v[68:71], v146 offset:96
	ds_read2st64_b64 v[88:91], v2 offset0:2 offset1:3
	s_waitcnt lgkmcnt(0)
	v_lshlrev_b32_e32 v92, 16, v84
	v_and_b32_e32 v93, 0xffff0000, v84
	v_lshlrev_b32_e32 v84, 16, v85
	v_and_b32_e32 v85, 0xffff0000, v85
	v_pk_fma_f32 v[84:85], v[54:55], v[82:83], v[84:85]
	v_lshlrev_b32_e32 v54, 16, v86
	v_and_b32_e32 v55, 0xffff0000, v86
	v_pk_fma_f32 v[54:55], v[56:57], v[76:77], v[54:55]
	v_lshlrev_b32_e32 v56, 16, v87
	v_and_b32_e32 v57, 0xffff0000, v87
	v_pk_fma_f32 v[56:57], v[58:59], v[78:79], v[56:57]
	v_lshlrev_b32_e32 v58, 16, v88
	v_and_b32_e32 v59, 0xffff0000, v88
	v_pk_fma_f32 v[58:59], v[60:61], v[72:73], v[58:59]
	v_lshlrev_b32_e32 v60, 16, v89
	v_and_b32_e32 v61, 0xffff0000, v89
	ds_read2st64_b64 v[86:89], v2 offset0:4 offset1:5
	v_pk_fma_f32 v[60:61], v[62:63], v[74:75], v[60:61]
	v_lshlrev_b32_e32 v62, 16, v90
	v_and_b32_e32 v63, 0xffff0000, v90
	v_pk_fma_f32 v[52:53], v[52:53], v[80:81], v[92:93]
	v_pk_fma_f32 v[62:63], v[64:65], v[68:69], v[62:63]
	v_lshlrev_b32_e32 v64, 16, v91
	v_and_b32_e32 v65, 0xffff0000, v91
	ds_read2st64_b64 v[90:93], v2 offset0:6 offset1:7
	v_pk_fma_f32 v[64:65], v[66:67], v[70:71], v[64:65]
	s_waitcnt lgkmcnt(0)
	v_lshlrev_b32_e32 v66, 16, v86
	v_and_b32_e32 v67, 0xffff0000, v86
	v_pk_fma_f32 v[66:67], v[36:37], v[80:81], v[66:67]
	v_lshlrev_b32_e32 v36, 16, v87
	v_and_b32_e32 v37, 0xffff0000, v87
	v_pk_fma_f32 v[86:87], v[38:39], v[82:83], v[36:37]
	v_lshlrev_b32_e32 v36, 16, v88
	v_and_b32_e32 v37, 0xffff0000, v88
	v_pk_fma_f32 v[94:95], v[40:41], v[76:77], v[36:37]
	v_lshlrev_b32_e32 v36, 16, v89
	v_and_b32_e32 v37, 0xffff0000, v89
	v_pk_fma_f32 v[88:89], v[42:43], v[78:79], v[36:37]
	v_lshlrev_b32_e32 v36, 16, v90
	v_and_b32_e32 v37, 0xffff0000, v90
	v_pk_fma_f32 v[44:45], v[44:45], v[72:73], v[36:37]
	v_lshlrev_b32_e32 v36, 16, v91
	v_and_b32_e32 v37, 0xffff0000, v91
	v_pk_fma_f32 v[46:47], v[46:47], v[74:75], v[36:37]
	v_lshlrev_b32_e32 v36, 16, v92
	v_and_b32_e32 v37, 0xffff0000, v92
	v_pk_fma_f32 v[48:49], v[48:49], v[68:69], v[36:37]
	ds_read2st64_b64 v[36:39], v2 offset0:8 offset1:9
	v_lshlrev_b32_e32 v40, 16, v93
	v_and_b32_e32 v41, 0xffff0000, v93
	v_pk_fma_f32 v[50:51], v[50:51], v[70:71], v[40:41]
	ds_read2st64_b64 v[40:43], v2 offset0:10 offset1:11
	s_waitcnt lgkmcnt(0)
	v_lshlrev_b32_e32 v90, 16, v36
	v_and_b32_e32 v91, 0xffff0000, v36
	v_pk_fma_f32 v[90:91], v[20:21], v[80:81], v[90:91]
	v_lshlrev_b32_e32 v20, 16, v37
	v_and_b32_e32 v21, 0xffff0000, v37
	v_pk_fma_f32 v[36:37], v[22:23], v[82:83], v[20:21]
	v_lshlrev_b32_e32 v20, 16, v38
	v_and_b32_e32 v21, 0xffff0000, v38
	v_pk_fma_f32 v[92:93], v[24:25], v[76:77], v[20:21]
	v_lshlrev_b32_e32 v20, 16, v39
	v_and_b32_e32 v21, 0xffff0000, v39
	v_pk_fma_f32 v[38:39], v[26:27], v[78:79], v[20:21]
	v_lshlrev_b32_e32 v20, 16, v40
	v_and_b32_e32 v21, 0xffff0000, v40
	v_pk_fma_f32 v[28:29], v[28:29], v[72:73], v[20:21]
	v_lshlrev_b32_e32 v20, 16, v41
	v_and_b32_e32 v21, 0xffff0000, v41
	v_pk_fma_f32 v[30:31], v[30:31], v[74:75], v[20:21]
	v_lshlrev_b32_e32 v20, 16, v42
	v_and_b32_e32 v21, 0xffff0000, v42
	v_pk_fma_f32 v[32:33], v[32:33], v[68:69], v[20:21]
	ds_read2st64_b64 v[20:23], v2 offset0:12 offset1:13
	v_lshlrev_b32_e32 v24, 16, v43
	v_and_b32_e32 v25, 0xffff0000, v43
	v_pk_fma_f32 v[34:35], v[34:35], v[70:71], v[24:25]
	ds_read2st64_b64 v[24:27], v2 offset0:14 offset1:15
	s_waitcnt lgkmcnt(0)
	v_lshlrev_b32_e32 v40, 16, v20
	v_and_b32_e32 v41, 0xffff0000, v20
	v_lshlrev_b32_e32 v20, 16, v21
	v_and_b32_e32 v21, 0xffff0000, v21
	v_pk_fma_f32 v[6:7], v[6:7], v[82:83], v[20:21]
	v_lshlrev_b32_e32 v20, 16, v22
	v_and_b32_e32 v21, 0xffff0000, v22
	v_pk_fma_f32 v[8:9], v[8:9], v[76:77], v[20:21]
	v_lshlrev_b32_e32 v20, 16, v23
	v_and_b32_e32 v21, 0xffff0000, v23
	v_pk_fma_f32 v[10:11], v[10:11], v[78:79], v[20:21]
	v_lshlrev_b32_e32 v20, 16, v24
	v_and_b32_e32 v21, 0xffff0000, v24
	v_pk_fma_f32 v[12:13], v[12:13], v[72:73], v[20:21]
	v_lshlrev_b32_e32 v20, 16, v25
	v_and_b32_e32 v21, 0xffff0000, v25
	v_mov_b32_e32 v142, v1
	v_pk_fma_f32 v[14:15], v[14:15], v[74:75], v[20:21]
	v_lshlrev_b32_e32 v20, 16, v26
	v_and_b32_e32 v21, 0xffff0000, v26
	s_waitcnt vmcnt(0)
	s_barrier
; __device__ __forceinline__ float gate_of(const Params& p, const LaneId& L, int b) { return sigmoid_f(ldbf(p32(p.P, (unsigned)(L.tq * LDP + C_GT + L.h * 3 + b)))); }
; __device__ __forceinline__ void park_o(const f32x16* o, char* pk, int lane) {
; #pragma unroll
;   for (int d0 = 0; d0 < 4; ++d0)
; #pragma unroll
;     for (int a = 0; a < 4; ++a) { u32x2 w = {cvtpk(o[d0][4 * a], o[d0][4 * a + 1]), cvtpk(o[d0][4 * a + 2], o[d0][4 * a + 3])};
;       *reinterpret_cast<u32x2*>(pk + ((d0 * 4 + a) * 64 + lane) * 8) = w; }
; }
; __device__ void nsa_item(const Params& p, int qb, int g, char* smem) {
;     ...
;     const LaneId L = lane_id(q0, g);
;     park_o(o, smem + NSA_IMP + L.wid * 8192, L.lane);
; #pragma unroll
;     for (int d0 = 0; d0 < 4; ++d0) o[d0] = f32x16{};
;     const int first = (qb < 8) ? 8 - qb : 0;
;     nsa_single<2>(p, L, q0, g, 9 - first, first, smem, qr, gate_of(p, L, 2), o);
	v_pk_fma_f32 v[16:17], v[16:17], v[68:69], v[20:21]
	v_and_b32_e32 v26, 3, v142
	v_lshlrev_b32_e32 v20, 16, v27
	v_and_b32_e32 v21, 0xffff0000, v27
	v_ashrrev_i32_e32 v24, 6, v142
	v_or_b32_e32 v27, s17, v26
	v_pk_fma_f32 v[4:5], v[4:5], v[80:81], v[40:41]
	v_and_b32_e32 v25, 63, v142
	v_add_u32_e32 v2, 1, v27
	v_lshlrev_b32_e32 v42, 3, v24
	v_cvt_f32_u32_e32 v40, v2
	v_add_u32_e32 v2, s5, v42
	v_lshl_add_u32 v144, v24, 13, v179
	v_lshlrev_b32_e32 v145, 3, v25
	v_cvt_pk_bf16_f32 v4, v4, v5
	v_cvt_pk_bf16_f32 v5, v6, v7
	v_cvt_pk_bf16_f32 v6, v8, v9
	v_bfe_u32 v8, v142, 2, 3
	v_pk_fma_f32 v[18:19], v[18:19], v[70:71], v[20:21]
	v_cvt_pk_bf16_f32 v20, v52, v53
	v_or_b32_e32 v52, v144, v145
	v_cvt_pk_bf16_f32 v7, v10, v11
	v_or_b32_e32 v2, v2, v8
	ds_write2st64_b64 v52, v[4:5], v[6:7] offset0:12 offset1:13
	v_cvt_pk_bf16_f32 v4, v12, v13
	v_cvt_pk_bf16_f32 v5, v14, v15
	v_cvt_pk_bf16_f32 v6, v16, v17
	v_cvt_pk_bf16_f32 v7, v18, v19
	v_mul_lo_u32 v2, v2, s25
	ds_write2st64_b64 v52, v[4:5], v[6:7] offset0:14 offset1:15
	v_mad_u64_u32 v[4:5], s[0:1], v27, 3, v[2:3]
	s_sub_i32 s18, 11, s16
	v_lshl_add_u32 v2, v4, 1, v192
	s_lshl_b64 s[12:13], s[18:19], 22
	global_load_ushort v146, v2, s[46:47]
	s_add_u32 s0, s34, s12
	v_lshrrev_b32_e32 v5, 5, v142
	v_ashrrev_i32_e32 v2, 4, v142
	s_addc_u32 s1, s35, s13
	s_sub_i32 s18, 15, s16
	v_and_b32_e32 v4, 15, v142
	v_and_b32_e32 v6, 8, v5
	v_and_b32_e32 v7, 7, v2
	s_lshl_b64 s[10:11], s[18:19], 22
	v_bitop3_b32 v7, v7, v4, v6 bitop3:0x36
	v_lshlrev_b32_e32 v2, 8, v2
	v_cvt_pk_bf16_f32 v21, v84, v85
	v_cvt_pk_bf16_f32 v22, v54, v55
	v_cvt_pk_bf16_f32 v23, v56, v57
	s_add_u32 s2, s34, s10
	v_lshl_or_b32 v2, v7, 4, v2
	v_add_u32_e32 v7, 0x200, v142
	ds_write2st64_b64 v52, v[20:21], v[22:23] offset1:1
	v_cvt_pk_bf16_f32 v20, v58, v59
	v_cvt_pk_bf16_f32 v21, v60, v61
	v_cvt_pk_bf16_f32 v22, v62, v63
	v_cvt_pk_bf16_f32 v23, v64, v65
	s_addc_u32 s3, s35, s11
	s_lshl_b32 s8, s15, 14
	v_ashrrev_i32_e32 v7, 4, v7
	ds_write2st64_b64 v52, v[20:21], v[22:23] offset0:2 offset1:3
	v_cvt_pk_bf16_f32 v20, v66, v67
	v_cvt_pk_bf16_f32 v21, v86, v87
	v_cvt_pk_bf16_f32 v22, v94, v95
	v_cvt_pk_bf16_f32 v23, v88, v89
	s_add_u32 s0, s0, s8
	v_readfirstlane_b32 s9, v142
	v_and_b32_e32 v9, 7, v7
	ds_write2st64_b64 v52, v[20:21], v[22:23] offset0:4 offset1:5
	v_cvt_pk_bf16_f32 v20, v44, v45
	v_cvt_pk_bf16_f32 v21, v46, v47
	v_cvt_pk_bf16_f32 v22, v48, v49
	v_cvt_pk_bf16_f32 v23, v50, v51
	s_addc_u32 s1, s1, 0
	s_lshl_b32 s9, s9, 4
	v_bitop3_b32 v4, v9, v4, v6 bitop3:0x36
	v_lshlrev_b32_e32 v6, 8, v7
	v_lshrrev_b32_e32 v10, 1, v142
	ds_write2st64_b64 v52, v[20:21], v[22:23] offset0:6 offset1:7
	v_cvt_pk_bf16_f32 v20, v90, v91
	v_cvt_pk_bf16_f32 v21, v36, v37
	v_cvt_pk_bf16_f32 v22, v92, v93
	v_cvt_pk_bf16_f32 v23, v38, v39
	s_and_b32 s9, s9, 0xfffffc00
	v_lshl_or_b32 v4, v4, 4, v6
	v_and_b32_e32 v6, 0x60, v142
	v_lshlrev_b32_e32 v7, 3, v142
	v_lshrrev_b32_e32 v9, 4, v142
	v_and_b32_e32 v10, 8, v10
	ds_write2st64_b64 v52, v[20:21], v[22:23] offset0:8 offset1:9
	v_cvt_pk_bf16_f32 v20, v28, v29
	v_cvt_pk_bf16_f32 v21, v30, v31
	v_cvt_pk_bf16_f32 v22, v32, v33
	v_cvt_pk_bf16_f32 v23, v34, v35
	s_mov_b32 m0, s9
	v_and_or_b32 v6, v7, 24, v6
	v_bfe_u32 v7, v142, 2, 2
	v_and_b32_e32 v5, 4, v5
	v_and_or_b32 v9, v9, 48, v10
	ds_write2st64_b64 v52, v[20:21], v[22:23] offset0:10 offset1:11
	global_load_lds_dwordx4 v2, s[0:1]
	s_add_i32 m0, s9, 0x2000
	v_or3_b32 v5, v5, v7, v9
	global_load_lds_dwordx4 v4, s[0:1]
	s_add_u32 s0, s2, s8
	v_lshlrev_b32_e32 v6, 1, v6
	v_lshlrev_b32_e32 v9, 8, v5
	s_addc_u32 s1, s3, 0
	v_or_b32_e32 v5, v9, v6
	s_add_i32 m0, s9, 0x8000
	s_movk_i32 s2, 0x2000
	global_load_lds_dwordx4 v5, s[0:1]
	v_bitop3_b32 v6, v9, s2, v6 bitop3:0x36
	s_add_i32 m0, s9, 0xa000
	v_mul_f32_e32 v43, -0.5, v40
	global_load_lds_dwordx4 v6, s[0:1]
	v_readlane_b32 s98, v252, 49
	v_readlane_b32 s99, v252, 50
	s_nop 0
	s_and_saveexec_b64 s[100:101], s[98:99]
	s_cbranch_execz .Lpf_skip2
	v_readlane_b32 s98, v252, 47
	v_readlane_b32 s99, v252, 48
	v_mov_b32_e32 v250, 1
	v_mov_b32_e32 v249, 0
	s_nop 5
	global_atomic_add v166, v249, v250, s[98:99] sc0
; __device__ __forceinline__ int v_rd_base(int lane) { return ((lane & 3) << 3) | (((lane >> 2) & 3) << 6) | (((lane >> 4) & 1) << 5) | (((lane >> 5) & 1) << 8); }
; __device__ __forceinline__ LaneId lane_id(int q0, int g) {
;   LaneId L; int t = threadIdx.x; asm volatile("" : "+v"(t) :: "memory");
;     ...
;   L.tq = q0 + L.wid * 8 + L.qi; L.sl2 = exp2f(-0.5f * (float)(L.h + 1)) * LOG2E; return L;
; }
; template <int MODE>
; __device__ __forceinline__ void nsa_single(const Params& p, const LaneId& L, int q0, int g, int ntiles, int first, char* smem, const bf16x8* qr, float gate, f32x16* o) {
;   const int NEG = -100000;
;   const unsigned char* ulist = (const unsigned char*)(smem + NSA_LIST);
;   const unsigned* mysel = (const unsigned*)(smem + NSA_SEL) + (L.wid * 8 + L.qi) * 8;
;   float* fac = (float*)(smem + NSA_FAC) + L.wid * 32;
;   char* pk = smem + NSA_IMP + L.wid * 8192;
;   const bf16* Kg; const bf16* Vg; const int ld = 128;
;   if (MODE == 1) { Kg = p.kvh + (long)(0 + g) * T * 128; Vg = p.kvh + (long)(4 + g) * T * 128; }
;   else { Kg = p.kvh + (long)(8 + g) * T * 128; Vg = p.kvh + (long)(12 + g) * T * 128; }
;   auto tile_row = [&](int i) -> int { const int ii = ntiles - 1 - i; if (MODE == 1) return __builtin_amdgcn_readfirstlane((int)ulist[ii]) * 64; return q0 - 512 + 64 * (first + ii); };
;   const int vb0 = (int)(uintptr_t)(smem + NSA_V0) + v_rd_base(L.lane);
;   float m = -1e30f, l = 0.f;
;   if (ntiles > 0) { const int row = tile_row(0); dma_k(Kg + (long)row * ld, ld, smem + NSA_K0, L.tid); dma_v(Vg + (long)row * ld, ld, smem + NSA_V0, L.tid); }
.Lpf_skip2:
	s_mov_b64 exec, s[100:101]
	s_mov_b32 s0, 0xc2fc0000
	v_cmp_gt_f32_e32 vcc, s0, v43
	v_bfe_u32 v41, v142, 5, 1
	v_lshlrev_b32_e32 v15, 2, v41
	v_cndmask_b32_e32 v5, 0, v180, vcc
	v_fmac_f32_e32 v5, -0.5, v40
	v_exp_f32_e32 v5, v5
	v_cndmask_b32_e32 v7, 0, v181, vcc
	v_cvt_f32_ubyte0_e32 v16, v15
	v_and_or_b32 v10, v142, 7, v10
	v_ldexp_f32 v5, v5, v7
	v_mul_f32_e32 v132, 0x3fb8aa3b, v5
	v_mul_f32_e32 v150, v132, v16
	v_lshlrev_b32_e32 v16, 4, v41
	v_lshlrev_b32_e32 v10, 4, v10
	s_movk_i32 s2, 0x60
	v_bitop3_b32 v155, v10, v16, s2 bitop3:0x1e
	s_movk_i32 s2, 0x80
	v_bitop3_b32 v156, v10, v16, s2 bitop3:0x1e
	s_movk_i32 s2, 0xa0
	v_bitop3_b32 v157, v10, v16, s2 bitop3:0x1e
	s_movk_i32 s2, 0xc0
	v_bitop3_b32 v158, v10, v16, s2 bitop3:0x1e
	s_movk_i32 s2, 0xe0
	v_bitop3_b32 v159, v10, v16, s2 bitop3:0x1e
	s_min_u32 s2, s15, 8
	s_lshl_b32 s24, s2, 14
	s_andn2_b32 s2, 0xff, s14
	v_sub_u32_e64 v5, 8, s15 clamp
	s_addk_i32 s24, 0x4000
	s_lshl_b32 s18, s2, 14
	v_readlane_b32 s14, v252, 51
	v_sub_u32_e32 v149, 9, v5
	v_lshlrev_b32_e32 v5, 4, v142
	s_add_u32 s2, s14, s12
	v_readlane_b32 s12, v252, 52
	v_and_b32_e32 v13, 0xc0, v5
	v_mov_b32_e32 v5, v3
	v_xor_b32_e32 v152, v10, v16
	v_bitop3_b32 v153, v10, v16, 32 bitop3:0x1e
	v_bitop3_b32 v154, v10, v16, 64 bitop3:0x1e
	v_lshlrev_b32_e32 v10, 1, v142
	s_addc_u32 s3, s12, s13
	v_lshl_add_u64 v[134:135], s[2:3], 0, v[2:3]
	v_lshl_add_u64 v[136:137], s[2:3], 0, v[4:5]
	v_and_b32_e32 v2, 0xc0, v10
	v_lshlrev_b32_e32 v4, 4, v26
	s_add_u32 s2, s14, s10
	v_and_b32_e32 v11, 31, v142
	v_lshl_add_u32 v12, v24, 7, v189
	v_and_b32_e32 v14, 0x118, v145
	v_or3_b32 v2, v9, v2, v4
	s_addc_u32 s3, s12, s11
	v_mov_b32_e32 v7, v3
	v_lshlrev_b32_e32 v151, 8, v11
	v_lshl_add_u32 v148, v11, 2, v12
	v_or_b32_e32 v147, v12, v16
	v_and_or_b32 v11, v10, 32, v14
	v_lshl_add_u64 v[138:139], s[2:3], 0, v[2:3]
	v_or_b32_e32 v2, v8, v42
	v_mov_b32_e32 v16, v3
	v_mov_b32_e32 v17, v3
	v_cmp_gt_u32_e64 s[8:9], 32, v25
	v_or3_b32 v160, v13, v11, s23
	v_lshl_add_u64 v[140:141], s[2:3], 0, v[6:7]
	v_sub_u32_e32 v161, v2, v15
	v_sub_u32_e32 v162, 0, v2
	v_mov_b32_e32 v2, v3
	v_mov_b32_e32 v4, v3
	v_mov_b32_e32 v6, v3
	v_mov_b32_e32 v8, v3
	v_mov_b32_e32 v9, v3
	v_mov_b32_e32 v10, v3
	v_mov_b32_e32 v11, v3
	v_mov_b32_e32 v12, v3
	v_mov_b32_e32 v13, v3
	v_mov_b32_e32 v14, v3
	v_mov_b32_e32 v15, v3
	v_mov_b64_e32 v[66:67], v[16:17]
	v_mov_b64_e32 v[50:51], v[16:17]
	v_mov_b64_e32 v[34:35], v[16:17]
	v_mov_b64_e32 v[64:65], v[14:15]
	v_mov_b64_e32 v[62:63], v[12:13]
	v_mov_b64_e32 v[60:61], v[10:11]
	v_mov_b64_e32 v[58:59], v[8:9]
	v_mov_b64_e32 v[56:57], v[6:7]
	v_mov_b64_e32 v[54:55], v[4:5]
	v_mov_b64_e32 v[52:53], v[2:3]
	v_mov_b64_e32 v[48:49], v[14:15]
	v_mov_b64_e32 v[46:47], v[12:13]
	v_mov_b64_e32 v[44:45], v[10:11]
	v_mov_b64_e32 v[42:43], v[8:9]
	v_mov_b64_e32 v[40:41], v[6:7]
	v_mov_b64_e32 v[38:39], v[4:5]
	v_mov_b64_e32 v[36:37], v[2:3]
	v_mov_b64_e32 v[32:33], v[14:15]
	v_mov_b64_e32 v[30:31], v[12:13]
	v_mov_b64_e32 v[28:29], v[10:11]
	v_mov_b64_e32 v[26:27], v[8:9]
	v_mov_b64_e32 v[24:25], v[6:7]
	v_mov_b64_e32 v[22:23], v[4:5]
	v_mov_b64_e32 v[20:21], v[2:3]
	v_mov_b64_e32 v[18:19], v[16:17]
	s_mov_b32 s0, 1
	s_mov_b32 s1, 0
	v_mov_b32_e32 v133, v132
	v_mov_b32_e32 v143, 0
	v_mov_b32_e32 v165, 0xf149f2ca
	v_mov_b64_e32 v[16:17], v[14:15]
	v_mov_b64_e32 v[14:15], v[12:13]
	v_mov_b64_e32 v[12:13], v[10:11]
	v_mov_b64_e32 v[10:11], v[8:9]
	v_mov_b64_e32 v[8:9], v[6:7]
	v_mov_b64_e32 v[6:7], v[4:5]
	v_mov_b64_e32 v[4:5], v[2:3]
	v_mov_b32_e32 v226, 0
	v_mul_f32_e32 v227, 0x40faf232, v132
	v_mul_f32_e32 v228, 0x417af232, v132
	v_mul_f32_e32 v229, 0x41bc35a6, v132
	v_mul_f32_e32 v230, 0x427af232, v132
	v_mul_f32_e32 v231, 0x428d283c, v132
	v_mul_f32_e32 v232, 0x429cd760, v132
	v_mul_f32_e32 v233, 0x42ac8683, v132
	v_mul_f32_e32 v234, 0x42faf232, v132
	v_mul_f32_e32 v235, 0x430550ab, v132
	v_mul_f32_e32 v236, 0x430d283c, v132
	v_mul_f32_e32 v237, 0x4314ffce, v132
	v_mul_f32_e32 v238, 0x433c35a6, v132
	v_mul_f32_e32 v239, 0x43440d37, v132
	v_mul_f32_e32 v240, 0x434be4c9, v132
	v_mul_f32_e32 v241, 0x4353bc5b, v132
	s_branch .LBB0_342

; __device__ __forceinline__ float ldbf(const bf16* p) { return bf2f(*reinterpret_cast<const unsigned short*>(p)); }
; __device__ __forceinline__ float sigmoid_f(float z) { return 1.f / (1.f + __expf(-z)); }
; __device__ __forceinline__ const bf16* p32(const bf16* base, unsigned elem_off) { return (const bf16*)((const char*)base + (size_t)(elem_off * 2u)); }
; __device__ __forceinline__ float gate_of(const Params& p, const LaneId& L, int b) { return sigmoid_f(ldbf(p32(p.P, (unsigned)(L.tq * LDP + C_GT + L.h * 3 + b)))); }
; template <int MODE>
; __device__ __forceinline__ void nsa_single(const Params& p, const LaneId& L, int q0, int g, int ntiles, int first, char* smem, const bf16x8* qr, float gate, f32x16* o) {
;     ...
;   l = half_swap_sum(l);
;   { const float f = (l > 0.f) ? gate / l : 0.f; f32x4 f4[4]; row_bcast(fac, L, f, f4); unpark_fma(o, pk, L.lane, f4); }
.LBB0_361:
	v_mov_b32_e32 v251, v166
	v_mov_b32_e32 v165, v143
	s_nop 1
	v_permlane32_swap_b32_e32 v143, v165
	s_and_saveexec_b64 s[10:11], s[8:9]
	s_cbranch_execz .LBB0_239
	v_lshlrev_b32_e32 v2, 16, v146
	v_mul_f32_e32 v2, 0xbfb8aa3b, v2
	v_exp_f32_e32 v142, v2
	s_nop 0
	v_pk_add_f32 v[68:69], v[142:143], v[164:165]
	s_nop 0
	v_div_scale_f32 v2, s[0:1], v68, v68, 1.0
	v_rcp_f32_e32 v70, v2
	v_div_scale_f32 v71, vcc, 1.0, v68, 1.0
	v_fma_f32 v72, -v2, v70, 1.0
	v_fmac_f32_e32 v70, v72, v70
	v_mul_f32_e32 v72, v71, v70
	v_fma_f32 v73, -v2, v72, v71
	v_fmac_f32_e32 v72, v73, v70
	v_fma_f32 v2, -v2, v72, v71
	v_div_fmas_f32 v2, v2, v70, v72
	v_div_fixup_f32 v2, v2, v68, 1.0
	v_div_scale_f32 v68, s[0:1], v69, v69, v2
	v_rcp_f32_e32 v70, v68
	v_div_scale_f32 v71, vcc, v2, v69, v2
	v_fma_f32 v72, -v68, v70, 1.0
	v_fmac_f32_e32 v70, v72, v70
	v_mul_f32_e32 v72, v71, v70
	v_fma_f32 v73, -v68, v72, v71
	v_fmac_f32_e32 v72, v73, v70
	v_fma_f32 v68, -v68, v72, v71
	v_div_fmas_f32 v68, v68, v70, v72
	v_div_fixup_f32 v2, v68, v69, v2
	v_cmp_lt_f32_e32 vcc, 0, v69
	s_nop 1
	v_cndmask_b32_e32 v2, 0, v2, vcc
	ds_write_b32 v148, v2
	s_branch .LBB0_239
